# window prologue: accumulator init, loop constants and the first tile's scalar head and prefetch loads moved ahead of the prologue's second barrier
# speedup vs baseline: 1.0050x; 1.0050x over previous
.LBB0_487:
	v_exp_f32_e32 v18, v227
	v_cmp_eq_u32_e32 vcc, 0, v226
	v_lshlrev_b32_e32 v16, 3, v16
	s_cmp_lt_i32 s27, -3
	v_cndmask_b32_e32 v198, 0, v18, vcc
	s_waitcnt vmcnt(0)
	ds_write_b128 v195, v[184:187] offset:9216
	ds_write_b128 v195, v[180:183] offset:18432
	s_waitcnt lgkmcnt(0)
	s_cbranch_scc1 .Lw403b
	s_min_u32 s0, s7, 0x80
	v_lshlrev_b32_e32 v18, 1, v16
	v_mov_b32_e32 v19, v1
	s_add_i32 s4, s4, s0
	v_mov_b32_e32 v110, v1
	v_mov_b32_e32 v111, v1
	v_lshl_add_u64 v[192:193], v[14:15], 0, v[18:19]
	v_mad_i32_i24 v14, v226, -4, s4
	s_movk_i32 s1, 0xff04
	s_sub_i32 s0, s7, s0
	v_mov_b32_e32 v96, v1
	v_mov_b32_e32 v97, v1
	v_mov_b32_e32 v98, v1
	v_mov_b32_e32 v99, v1
	v_mov_b32_e32 v100, v1
	v_mov_b32_e32 v101, v1
	v_mov_b32_e32 v102, v1
	v_mov_b32_e32 v103, v1
	v_mov_b32_e32 v104, v1
	v_mov_b32_e32 v105, v1
	v_mov_b32_e32 v106, v1
	v_mov_b32_e32 v107, v1
	v_mov_b32_e32 v108, v1
	v_mov_b32_e32 v109, v1
	v_mov_b64_e32 v[126:127], v[110:111]
	v_lshl_add_u64 v[190:191], s[12:13], 0, v[18:19]
	s_add_i32 s18, s27, 4
	s_add_i32 s19, s20, 0xffffff9f
	s_addk_i32 s20, 0x41
	s_mov_b32 s8, 0
	s_sub_i32 s21, 0, s27
	v_add3_u32 v197, v14, v17, s1
	s_add_i32 s7, s0, 64
	v_mov_b64_e32 v[124:125], v[108:109]
	v_mov_b64_e32 v[122:123], v[106:107]
	v_mov_b64_e32 v[120:121], v[104:105]
	v_mov_b64_e32 v[118:119], v[102:103]
	v_mov_b64_e32 v[116:117], v[100:101]
	v_mov_b64_e32 v[114:115], v[98:99]
	v_mov_b64_e32 v[112:113], v[96:97]
	s_add_i32 s0, s8, 2
	s_cmp_lt_i32 s0, s18
	s_cselect_b64 s[12:13], -1, 0
	s_cmp_ge_i32 s0, s18
	s_cbranch_scc1 .Lwp491
	s_add_i32 s1, s6, s8
	s_add_i32 s4, s21, s8
	s_add_i32 s1, s1, 2
	s_add_i32 s4, s4, 34
	s_cmp_lt_i32 s0, s27
	s_cselect_b32 s0, s1, s4
	v_lshl_add_u32 v14, s0, 6, v194
	v_ashrrev_i32_e32 v15, 31, v14
	v_lshlrev_b64 v[14:15], 9, v[14:15]
	v_lshl_add_u64 v[14:15], v[190:191], 0, v[14:15]
	global_load_dwordx4 v[184:187], v[14:15], off

.Lwp495:
	s_bitcmp1_b32 s22, 0
	s_cselect_b32 s23, 0x2400, 0
	s_add_i32 s30, s23, 0
	s_bitcmp1_b32 s8, 0
	s_cselect_b32 s28, 0x2400, 0
	s_and_b64 s[4:5], s[2:3], s[14:15]
	s_add_i32 s29, s28, 0
	s_andn2_b64 vcc, exec, s[4:5]
	s_mov_b64 s[4:5], -1
	s_barrier
	s_cbranch_vccnz .LBB0_502
	s_branch .LBB0_513
.Lw403b:
	s_barrier
	s_branch .LBB0_403
.LBB0_489:
	s_add_i32 s0, s8, 2
	s_cmp_lt_i32 s0, s18
	s_cselect_b64 s[12:13], -1, 0
	s_cmp_ge_i32 s0, s18
	s_cbranch_scc1 .LBB0_491
	s_add_i32 s1, s6, s8
	s_add_i32 s4, s21, s8
	s_add_i32 s1, s1, 2
	s_add_i32 s4, s4, 34
	s_cmp_lt_i32 s0, s27
	s_cselect_b32 s0, s1, s4
	v_lshl_add_u32 v14, s0, 6, v194
	v_ashrrev_i32_e32 v15, 31, v14
	v_lshlrev_b64 v[14:15], 9, v[14:15]
	v_lshl_add_u64 v[14:15], v[190:191], 0, v[14:15]
	global_load_dwordx4 v[184:187], v[14:15], off
